# up-projection weights of layers 1-3 converted by the workgroups that have no 12th unit in the previous layer's up-GEMM phase (prologue converts only what layer 0 needs plus the small matrices)
# speedup vs baseline: 1.0076x; 1.0076x over previous
; #define LAS __attribute__((address_space(3)))
; __device__ __forceinline__ KP kp_fresh(KP k) { asm volatile("" : "+s"(k)); return k; }
; __device__ __forceinline__ int tid_fresh(int wid) { return wid * 64 + lane_id(); }
; __device__ __forceinline__ WTile wtile_decode(KP kp, int ti) {
;     ...
;     else              { const int q = ti - B6, lg = q / T_PG; loc = q % T_PG; w.src = kp->in[12] + (size_t)lg * 256 * 256; w.dst = (bf16*)(ws + W_POOL) + (size_t)lg * 256 * 256; w.K = 256; w.Nsrc = 256; nkt = 4; w.scale = kp->in[13] + lg * 256; w.kscale = kp->in[2] + (2 * (lg >> 2) + 1) * 1024 + (lg & 3) * 256; }
; __device__ __forceinline__ void prologue_weights(KP kp, LAS float* tile, int wid0) {
;     kp = kp_fresh(kp);
;     const int tid = tid_fresh(wid0);
;     int ti = blockIdx.x;
;     if (ti >= W_TILES) return;
;     WTile w = wtile_decode(kp, ti);
.LBB0_5:
	s_or_b64 exec, exec, s[2:3]
	s_waitcnt lgkmcnt(0)
	s_mov_b32 s56, 0
	s_mov_b32 s57, s33
	s_mov_b32 s58, s38
	s_movk_i32 s59, 0x16a0
	s_mov_b32 s60, 0
	s_movk_i32 s94, 0x1080
	s_movk_i32 s95, 0x1080
	s_mov_b32 s91, s33
.Lconv_entry:
	s_mov_b64 s[8:9], s[88:89]
	s_cmp_ge_i32 s57, s59
	v_mbcnt_lo_u32_b32 v14, -1, 0
	v_mbcnt_hi_u32_b32 v14, -1, v14
	s_cbranch_scc1 .LBB0_161
	s_load_dwordx2 s[14:15], s[8:9], 0x98
	s_cmpk_gt_i32 s91, 0x15ff
	s_cselect_b64 s[4:5], -1, 0
	s_and_b64 vcc, exec, s[4:5]
	s_cbranch_vccz .LBB0_13
	s_cmpk_gt_u32 s91, 0x20ff
	s_cbranch_scc0 .LBB0_14
	s_cmpk_gt_u32 s91, 0x227f
	s_cbranch_scc0 .LBB0_15
	s_cmpk_gt_u32 s91, 0x239f
	s_cbranch_scc0 .LBB0_16
	s_cmpk_gt_u32 s91, 0x249f
	s_cbranch_scc0 .LBB0_17
	s_cmpk_gt_u32 s91, 0x269f
	s_cbranch_scc0 .LBB0_18
	s_load_dwordx4 s[16:19], s[8:9], 0x60
	s_load_dwordx2 s[22:23], s[8:9], 0x10
	s_add_i32 s0, s91, 0xffffd960
	s_lshr_b32 s20, s0, 4
	s_mov_b32 s21, 0
	s_and_b32 s1, s91, 15
	s_lshl_b64 s[2:3], s[20:21], 18
	s_waitcnt lgkmcnt(0)
	s_add_u32 s2, s16, s2
	s_addc_u32 s3, s17, s3
	s_lshl_b64 s[10:11], s[20:21], 17
	s_add_u32 s10, s14, s10
	s_addc_u32 s11, s15, s11
	s_add_u32 s10, s10, 0x5140000
	s_addc_u32 s11, s11, 0
	s_lshl_b32 s20, s20, 8
	s_lshl_b64 s[12:13], s[20:21], 2
	s_add_u32 s12, s18, s12
	s_addc_u32 s13, s19, s13
	s_lshl_b32 s16, s0, 5
	s_and_b32 s20, s16, 0x7ffff800
	s_lshl_b64 s[16:17], s[20:21], 2
	s_add_u32 s16, s22, s16
	s_addc_u32 s17, s23, s17
	s_lshl_b32 s0, s0, 6
	s_and_b32 s0, s0, 0xc00
	s_add_u32 s0, s16, s0
	s_addc_u32 s17, s17, 0
	s_add_u32 s16, s0, 0x1000
	s_addc_u32 s17, s17, 0
	s_mov_b64 s[18:19], 0
	s_branch .LBB0_19

; __device__ __forceinline__ WTile wtile_decode(KP kp, int ti) {
;     ...
;     else if (ti < B6) { const int q = ti - B5, l = q / T_O; loc = q % T_O; w.src = kp->in[11] + (size_t)l * 1024 * 1024; w.dst = (bf16*)(ws + W_O + l * SZ_O); w.K = 1024; w.Nsrc = 1024; nkt = 16; }
.LBB0_19:
	s_andn2_b64 vcc, exec, s[18:19]
	s_cbranch_vccnz .LBB0_21
	s_load_dwordx2 s[2:3], s[8:9], 0x58
	s_add_i32 s0, s91, 0xffffdb60
	s_lshr_b32 s10, s0, 8
	s_mov_b32 s11, 0
	s_and_b32 s1, s0, 0xff
	s_lshl_b64 s[12:13], s[10:11], 22
	s_waitcnt lgkmcnt(0)
	s_add_u32 s2, s2, s12
	s_addc_u32 s3, s3, s13
	s_lshl_b64 s[10:11], s[10:11], 21
	s_add_u32 s0, s14, s10
	s_addc_u32 s11, s15, s11
	s_add_u32 s10, s0, 0x4d40000
	s_addc_u32 s11, s11, 0
	s_mov_b32 s22, 16
	s_mov_b64 s[16:17], 0
	s_movk_i32 s20, 0x400
	s_mov_b64 s[12:13], 0
	s_branch .LBB0_22

; __device__ __forceinline__ WTile wtile_decode(KP kp, int ti) {
;     ...
;     else if (ti < B5) { const int q = ti - B4, l = q / T_UKV; loc = q % T_UKV; w.src = kp->in[10] + (size_t)l * 256 * 2048; w.dst = (bf16*)(ws + W_UKV + l * SZ_UKV); w.K = 256; w.Nsrc = 2048; nkt = 4; w.kscale = kp->in[9] + l * 256; }
.LBB0_23:
	s_andn2_b64 vcc, exec, s[18:19]
	s_mov_b32 s0, s20
	s_cbranch_vccnz .LBB0_25
	s_load_dwordx4 s[16:19], s[8:9], 0x48
	s_add_i32 s0, s91, 0xffffdc60
	s_lshr_b32 s12, s0, 7
	s_mov_b32 s13, 0
	s_and_b32 s1, s0, 0x7f
	s_lshl_b64 s[2:3], s[12:13], 21
	s_waitcnt lgkmcnt(0)
	s_add_u32 s2, s18, s2
	s_addc_u32 s3, s19, s3
	s_lshl_b64 s[10:11], s[12:13], 20
	s_add_u32 s0, s14, s10
	s_addc_u32 s11, s15, s11
	s_add_u32 s10, s0, 0x4b40000
	s_addc_u32 s11, s11, 0
	s_lshl_b32 s12, s12, 8
	s_lshl_b64 s[12:13], s[12:13], 2
	s_add_u32 s16, s16, s12
	s_addc_u32 s17, s17, s13
	s_mov_b32 s22, 4
	s_mov_b64 s[12:13], 0
	s_movk_i32 s0, 0x100
	s_movk_i32 s20, 0x800

; __device__ __forceinline__ WTile wtile_decode(KP kp, int ti) {
;     ...
;     else if (ti < B4) { const int q = ti - B3, l = q / T_UQ; loc = q % T_UQ; w.src = kp->in[8] + (size_t)l * 384 * 1536; w.dst = (bf16*)(ws + W_UQ + l * SZ_UQ); w.K = 384; w.Nsrc = 1536; nkt = 6; w.map = 1; w.kscale = kp->in[7] + l * 384; }
.LBB0_26:
	s_andn2_b64 vcc, exec, s[18:19]
	s_mov_b32 s21, 0
	s_cbranch_vccnz .LBB0_28
	s_load_dwordx4 s[16:19], s[8:9], 0x38
	s_add_i32 s0, s91, 0xffffdd80
	s_add_i32 s1, s91, 0xffffdcf0
	s_cmpk_lt_u32 s0, 0x90
	s_cselect_b32 s1, s0, s1
	s_cmpk_gt_u32 s0, 0x8f
	s_cselect_b32 s0, 0x240000, 0
	s_cselect_b32 s10, 0x120000, 0
	s_cselect_b32 s12, 0x600, 0
	s_waitcnt lgkmcnt(0)
	s_add_u32 s2, s18, s0
	s_addc_u32 s3, s19, 0
	s_add_u32 s0, s14, s10
	s_addc_u32 s11, s15, 0
	s_add_u32 s10, s0, 0x4900000
	s_addc_u32 s11, s11, 0
	s_add_u32 s16, s16, s12
	s_movk_i32 s20, 0x600
	s_addc_u32 s17, s17, 0
	s_mov_b32 s22, 6
	s_mov_b64 s[12:13], 0
	s_movk_i32 s0, 0x180
	s_mov_b32 s21, 1

; __device__ __forceinline__ WTile wtile_decode(KP kp, int ti) {
;     ...
;     else if (ti < B3) { const int q = ti - B2, l = q / T_DQKV; loc = q % T_DQKV; w.src = kp->in[6] + (size_t)l * 1024 * 672; w.dst = (bf16*)(ws + W_DQKV + l * SZ_DQKV); w.K = 1024; w.Nsrc = 672; nkt = 16; w.kscale = kp->in[2] + (2 * l) * 1024; }
.LBB0_29:
	s_load_dwordx2 s[12:13], s[8:9], 0x10
	s_load_dwordx2 s[2:3], s[8:9], 0x30
	s_add_i32 s0, s91, 0xffffdf00
	s_add_i32 s1, s91, 0xffffde40
	s_cmpk_lt_u32 s0, 0xc0
	s_cselect_b32 s1, s0, s1
	s_cmpk_gt_u32 s0, 0xbf
	s_cselect_b32 s0, 0x2a0000, 0
	s_cselect_b32 s10, 0x180000, 0
	s_cselect_b32 s16, 0x2000, 0
	s_waitcnt lgkmcnt(0)
	s_add_u32 s2, s2, s0
	s_addc_u32 s3, s3, 0
	s_add_u32 s0, s14, s10
	s_addc_u32 s11, s15, 0
	s_add_u32 s10, s0, 0x4600000
	s_addc_u32 s11, s11, 0
	s_add_u32 s16, s12, s16
	s_mov_b32 s21, 0
	s_addc_u32 s17, s13, 0
	s_mov_b32 s22, 16
	s_mov_b64 s[12:13], 0
	s_movk_i32 s0, 0x400
	s_movk_i32 s20, 0x2a0

; __device__ __forceinline__ WTile wtile_decode(KP kp, int ti) {
;     ...
;     else if (ti < B2) { const int q = ti - B1, l = q / T_DOWN; loc = q % T_DOWN; w.src = kp->in[17] + (size_t)l * 2816 * 1024; w.dst = (bf16*)(ws + W_DOWN + l * SZ_DOWN); w.K = 2816; w.Nsrc = 1024; nkt = 44; }
.LBB0_31:
	s_add_i32 s0, s91, 0xea00
	s_and_b32 s1, s0, 0xffff
	s_mul_i32 s1, s1, 0xba2f
	s_load_dwordx2 s[2:3], s[8:9], 0x88
	s_lshr_b32 s10, s1, 25
	s_mul_i32 s1, s10, 0x2c0
	s_sub_i32 s0, s0, s1
	s_and_b32 s1, s0, 0xffff
	s_mul_i32 s0, s10, 0xb00000
	s_waitcnt lgkmcnt(0)
	s_add_u32 s2, s2, s0
	s_addc_u32 s3, s3, 0
	s_mul_i32 s10, s10, 0x580000
	s_add_u32 s0, s14, s10
	s_addc_u32 s11, s15, 0
	s_add_u32 s10, s0, 0x3000000
	s_mov_b32 s21, 0
	s_addc_u32 s11, s11, 0
	s_mov_b32 s22, 44
	s_mov_b64 s[16:17], 0
	s_movk_i32 s0, 0xb00
	s_movk_i32 s20, 0x400
	s_mov_b64 s[12:13], 0

; __device__ __forceinline__ WTile wtile_decode(KP kp, int ti) {
;     ...
;     if (ti < B1)      { const int l = ti / T_UP; loc = ti % T_UP; w.src = kp->in[14] + (size_t)l * 1024 * 5632; w.dst = (bf16*)(ws + W_UP + l * SZ_UP); w.K = 1024; w.Nsrc = 5632; nkt = 16; w.map = 2; w.kscale = kp->in[4] + l * 1024; }
;     ...
;     { const int ntiles_n = (ti < B1 ? T_UP : ti < B2 ? T_DOWN : ti < B3 ? T_DQKV : ti < B4 ? T_UQ : ti < B5 ? T_UKV : ti < B6 ? T_O : T_PG) / nkt;
;       w.n0 = (loc % ntiles_n) * 64; w.k0 = (loc / ntiles_n) * 64; }
.LBB0_33:
	s_mul_hi_i32 s0, s91, 0x2e8ba2e9
	s_load_dwordx2 s[2:3], s[8:9], 0x70
	s_load_dwordx2 s[12:13], s[8:9], 0x20
	s_lshr_b32 s1, s0, 31
	s_ashr_i32 s0, s0, 8
	s_add_i32 s0, s0, s1
	s_mul_i32 s1, s0, 0x580
	s_sub_i32 s1, s91, s1
	s_mul_i32 s11, s0, 0x1600000
	s_mul_hi_i32 s10, s0, 0x1600000
	s_waitcnt lgkmcnt(0)
	s_add_u32 s2, s2, s11
	s_addc_u32 s3, s3, s10
	s_mul_i32 s11, s0, 0xb00000
	s_mul_hi_i32 s10, s0, 0xb00000
	s_add_u32 s11, s14, s11
	s_addc_u32 s16, s15, s10
	s_add_u32 s10, s11, 0x400000
	s_addc_u32 s11, s16, 0
	s_lshl_b32 s16, s0, 10
	s_ashr_i32 s17, s16, 31
	s_lshl_b64 s[16:17], s[16:17], 2
	s_add_u32 s16, s12, s16
	s_mov_b32 s21, 2
	s_addc_u32 s17, s13, s17
	s_movk_i32 s20, 0x1600
	s_movk_i32 s0, 0x400
	s_mov_b64 s[12:13], 0
	s_mov_b32 s22, 16
.LBB0_34:
	s_andn2_b64 vcc, exec, s[4:5]
	s_movk_i32 s4, 0x580
	s_cbranch_vccnz .LBB0_37
	s_cmpk_lt_u32 s91, 0x2100
	s_movk_i32 s4, 0x2c0
	s_cbranch_scc1 .LBB0_37
	s_cmpk_lt_u32 s91, 0x26a0
	s_cselect_b32 s4, 0x100, 16
	s_cmpk_gt_u32 s91, 0x249f
	s_cselect_b32 s4, s4, 0x80
	s_cmpk_gt_u32 s91, 0x239f
	s_cselect_b32 s4, s4, 0x90
	s_cmpk_gt_u32 s91, 0x227f
	s_cselect_b32 s4, s4, 0xc0

; #define LAS __attribute__((address_space(3)))
; __device__ __forceinline__ KP kp_fresh(KP k) { asm volatile("" : "+s"(k)); return k; }
; __device__ __forceinline__ int tid_fresh(int wid) { return wid * 64 + lane_id(); }
; __device__ __forceinline__ void prologue_weights(KP kp, LAS float* tile, int wid0) {
;     kp = kp_fresh(kp);
;     const int tid = tid_fresh(wid0);
;     int ti = blockIdx.x;
;     if (ti >= W_TILES) return;
;     WTile w = wtile_decode(kp, ti);
;     float v[8];
;     wtile_load(w, tid, v);
;     int par = 0;
;     for (;;) {
;         LAS float* tb = tile + par * (64 * 65);
.LBB0_81:
	s_or_b64 exec, exec, s[4:5]
	s_waitcnt lgkmcnt(0)
	s_add_u32 s28, s14, 0x5140000
	s_addc_u32 s29, s15, 0
	s_add_u32 s30, s14, 0x4d40000
	s_addc_u32 s31, s15, 0
	s_add_u32 s34, s14, 0x4b40000
	s_addc_u32 s35, s15, 0
	s_add_u32 s36, s14, 0x4900000
	s_addc_u32 s37, s15, 0
	s_add_u32 s40, s14, 0x4600000
	s_addc_u32 s41, s15, 0
	s_add_u32 s42, s14, 0x3000000
	v_lshlrev_b32_e32 v10, 3, v14
	s_addc_u32 s43, s15, 0
	v_and_b32_e32 v10, 56, v10
	s_add_u32 s44, s14, 0x400000
	s_movk_i32 s2, 0x104
	v_ashrrev_i32_e32 v13, 3, v15
	v_mov_b32_e32 v11, 0
	s_addc_u32 s45, s15, 0
	v_and_or_b32 v12, v14, 31, 64
	v_mul_lo_u32 v22, v21, s2
	v_mul_u32_u24_e32 v23, 0x104, v10
	s_mov_b32 s15, 0
	v_lshlrev_b32_e32 v24, 2, v20
	s_movk_i32 s46, 0x3ff
	s_movk_i32 s47, 0x60
	v_lshlrev_b32_e32 v14, 1, v10
	s_mov_b32 s48, 0
	s_mov_b32 s49, s91
	v_mov_b32_e32 v40, 1.0
	v_mov_b32_e32 v41, 1.0
	v_mov_b32_e32 v42, 1.0
	v_mov_b32_e32 v43, 1.0
	v_mov_b32_e32 v44, 1.0
	v_mov_b32_e32 v45, 1.0
	v_mov_b32_e32 v46, 1.0
	v_mov_b32_e32 v47, 1.0
	v_mov_b32_e32 v48, 1.0
	s_branch .LBB0_83

; #define LAS __attribute__((address_space(3)))
; __device__ __forceinline__ WTile wtile_decode(KP kp, int ti) {
;     constexpr int T_UP = 1408, T_DOWN = 704, T_DQKV = 192, T_UQ = 144, T_UKV = 128, T_O = 256, T_PG = 16;
;     constexpr int B1 = 4 * T_UP, B2 = B1 + 4 * T_DOWN, B3 = B2 + 2 * T_DQKV, B4 = B3 + 2 * T_UQ, B5 = B4 + 2 * T_UKV, B6 = B5 + 2 * T_O;
;     unsigned char* ws = kp->ws; WTile w; w.scale = nullptr; w.kscale = nullptr; w.map = 0; int nkt, loc;
;     if (ti < B1)      { const int l = ti / T_UP; loc = ti % T_UP; w.src = kp->in[14] + (size_t)l * 1024 * 5632; w.dst = (bf16*)(ws + W_UP + l * SZ_UP); w.K = 1024; w.Nsrc = 5632; nkt = 16; w.map = 2; w.kscale = kp->in[4] + l * 1024; }
; __device__ __forceinline__ void prologue_weights(KP kp, LAS float* tile, int wid0) {
;     ...
;     for (;;) {
;         LAS float* tb = tile + par * (64 * 65);
; #pragma unroll
;         for (int i = 0; i < 8; ++i) tb[(i * 8 + (tid >> 6)) * 65 + (tid & 63)] = v[i];
;         __syncthreads();
;         const int tn = ti + (int)gridDim.x; const bool more = tn < W_TILES;
;         WTile wn = w;
;         if (more) { wn = wtile_decode(kp, tn); wtile_load(wn, tid, v); }
.LBB0_83:
	s_mul_i32 s2, s48, 0x4100
	s_add_i32 s13, s2, 0
	s_add_i32 s57, s57, s58
	s_cmpk_lt_i32 s57, 0x580
	s_cselect_b32 s50, s60, s94
	s_cmpk_lt_i32 s57, 0x840
	s_cselect_b32 s50, s50, s95
	s_add_i32 s50, s50, s57
	s_cmp_lt_i32 s57, s59
	s_cselect_b64 s[18:19], -1, 0
	s_cmp_ge_i32 s57, s59
	s_cselect_b64 s[16:17], -1, 0
	s_waitcnt vmcnt(0)
	v_mul_f32_e32 v2, v40, v2
	v_mul_f32_e32 v9, v40, v9
	v_mul_f32_e32 v4, v40, v4
	v_mul_f32_e32 v3, v40, v3
	v_mul_f32_e32 v6, v40, v6
	v_mul_f32_e32 v5, v40, v5
	v_mul_f32_e32 v8, v40, v8
	v_mul_f32_e32 v7, v40, v7
	v_mul_f32_e32 v2, v2, v41
	v_mul_f32_e32 v9, v9, v42
	v_mul_f32_e32 v4, v4, v43
	v_mul_f32_e32 v3, v3, v44
	v_mul_f32_e32 v6, v6, v45
	v_mul_f32_e32 v5, v5, v46
	v_mul_f32_e32 v8, v8, v47
	v_mul_f32_e32 v7, v7, v48
	v_add3_u32 v10, s13, v24, v22
	s_and_b64 vcc, exec, s[16:17]
	s_mov_b64 s[20:21], s[10:11]
	s_mov_b32 s14, s0
	s_mov_b32 s53, s12
	s_mov_b32 s52, s1
	ds_write_b32 v10, v2
	ds_write_b32 v10, v9 offset:2080
	ds_write_b32 v10, v4 offset:4160
	ds_write_b32 v10, v3 offset:6240
	ds_write_b32 v10, v6 offset:8320
	ds_write_b32 v10, v5 offset:10400
	ds_write_b32 v10, v8 offset:12480
	ds_write_b32 v10, v7 offset:14560
	s_waitcnt lgkmcnt(0)
	s_barrier
	s_cbranch_vccnz .LBB0_157
	s_cmpk_gt_i32 s50, 0x15ff
	s_cselect_b64 s[4:5], -1, 0
	s_mov_b64 s[26:27], -1
	s_and_b64 vcc, exec, s[4:5]
	s_cbranch_vccz .LBB0_106
	s_cmpk_gt_u32 s50, 0x20ff
	s_cbranch_scc0 .LBB0_102
	s_cmpk_gt_u32 s50, 0x227f
	s_cbranch_scc0 .LBB0_99
	s_cmpk_gt_u32 s50, 0x239f
	s_cbranch_scc0 .LBB0_96
	s_cmpk_gt_u32 s50, 0x249f
	s_cbranch_scc0 .LBB0_93
	s_cmpk_gt_u32 s50, 0x269f
	s_cbranch_scc0 .LBB0_91
	s_load_dwordx4 s[20:23], s[8:9], 0x60
	s_load_dwordx2 s[26:27], s[8:9], 0x10
	s_add_i32 s51, s50, 0xffffd960
	s_lshr_b32 s14, s51, 4
	s_and_b32 s52, s50, 15
	s_lshl_b64 s[2:3], s[14:15], 18
	s_waitcnt lgkmcnt(0)
	s_add_u32 s2, s20, s2
	s_addc_u32 s3, s21, s3
	s_lshl_b64 s[20:21], s[14:15], 17
	s_add_u32 s20, s28, s20
	s_addc_u32 s21, s29, s21
	s_lshl_b32 s14, s14, 8
	s_lshl_b64 s[24:25], s[14:15], 2
	s_add_u32 s24, s22, s24
	s_addc_u32 s25, s23, s25
	s_lshl_b32 s14, s51, 5
	s_and_b32 s14, s14, 0x7ffff800
	s_lshl_b64 s[22:23], s[14:15], 2
	s_add_u32 s14, s26, s22
	s_addc_u32 s22, s27, s23
	s_lshl_b32 s23, s51, 6
	s_and_b32 s23, s23, 0xc00
	s_add_u32 s14, s14, s23
	s_addc_u32 s23, s22, 0
	s_add_u32 s22, s14, 0x1000
	s_addc_u32 s23, s23, 0
	s_mov_b64 s[26:27], 0

; __device__ __forceinline__ KP kp_fresh(KP k) { asm volatile("" : "+s"(k)); return k; }
; __device__ __forceinline__ int tid_fresh(int wid) { return wid * 64 + lane_id(); }
; __device__ __forceinline__ void prologue_weights(KP kp, LAS float* tile, int wid0) {
;     ...
;     __syncthreads();
; }
; __device__ __forceinline__ void prologue_rope(KP kp, int wid0) {
;     kp = kp_fresh(kp); const int tid = tid_fresh(wid0);
;     float* rc = (float*)(kp->ws + WS_ROPE); float* rs = rc + LL * 16;
;     for (int i = blockIdx.x * 512 + tid; i < LL * 16; i += gridDim.x * 512) {
;         const int t = i >> 4, e = i & 15;
;         const float ang = (float)t * kp->inv_freq[e];
;         const double rev = (double)ang * 0.15915494309189535;
;         const float fr = (float)(rev - __builtin_rint(rev));
;         rc[i] = __builtin_amdgcn_cosf(fr); rs[i] = __builtin_amdgcn_sinf(fr);
.LBB0_161:
	s_cmp_lg_u32 s56, 0
	s_cbranch_scc1 .Lconv_ret
	s_lshl_b32 s0, s33, 9
	s_mov_b64 s[4:5], s[88:89]
	s_add_i32 s0, s61, s0
	v_mbcnt_lo_u32_b32 v3, -1, 0
	v_mbcnt_hi_u32_b32 v3, -1, v3
	s_nop 0
	v_add_u32_e32 v2, s0, v3
	s_mov_b32 s0, 0x8100
	v_cmp_gt_i32_e32 vcc, s0, v2
	s_and_saveexec_b64 s[2:3], vcc
	s_cbranch_execz .LBB0_164
	v_and_b32_e32 v3, 15, v3
	v_lshlrev_b32_e32 v3, 2, v3
	global_load_dword v4, v3, s[4:5] offset:160
	s_load_dwordx2 s[0:1], s[4:5], 0x98
	s_mov_b32 s12, 0x6dc9c883
	s_mov_b64 s[10:11], 0
	s_mov_b32 s13, 0x3fc45f30
	s_waitcnt lgkmcnt(0)
	s_add_u32 s4, s0, 0x100000
	s_addc_u32 s5, s1, 0
	s_add_u32 s8, s0, 0x120400
	s_addc_u32 s9, s1, 0
	s_lshl_b32 s0, s38, 9
	s_mov_b32 s1, 0x80ff
	s_waitcnt vmcnt(0)

; #define GSYNC() gsync(kp0, lds, wid0)
; __device__ __forceinline__ void xcd_barrier(const XcdBarrier& b, int tid) {
;     asm volatile("s_waitcnt vmcnt(0)" ::: "memory");
;     __syncthreads();
;     if (tid == 0) {
;         unsigned* bar = b.bar;
;         __builtin_amdgcn_s_waitcnt(0);
;         unsigned nloc = b.st[0], nx = b.st[1];
;         if (nloc == 0u) { xcd_barrier_complete(bar, b.x, nloc, nx); b.st[0] = nloc; b.st[1] = nx; }
; __global__ void __launch_bounds__(512, 2) hybrid_fwd(Params p_unused) {
;     ...
;                     pg8::gemm_phase<pg8::EpiConv, pg8::StaticOrder, true, true>(lds, g, S, E, wid0);
;                 }
;                 GSYNC();
.LBB0_624:
	s_waitcnt vmcnt(0)
	v_readlane_b32 s88, v255, 38
	v_readlane_b32 s89, v255, 39
	v_readlane_b32 s61, v255, 40
	s_movk_i32 s63, 0x50
	s_movk_i32 s90, 0xc00
	s_movk_i32 s84, 0xf7f0
	s_barrier
	v_readlane_b32 s0, v255, 41
	s_cmp_gt_u32 s0, 2
	s_cbranch_scc1 .Lconv_skip
	s_cmp_lt_u32 s33, 0x42
	s_cbranch_scc1 .Lconv_skip
	v_writelane_b32 v254, s24, 0
	v_writelane_b32 v254, s25, 1
	v_writelane_b32 v254, s26, 2
	v_writelane_b32 v254, s27, 3
	v_writelane_b32 v254, s28, 4
	v_writelane_b32 v254, s29, 5
	v_writelane_b32 v254, s30, 6
	v_writelane_b32 v254, s31, 7
	s_mov_b32 s56, 1
	s_sub_i32 s57, s33, 0x42
	s_movk_i32 s58, 0xbe
	s_movk_i32 s59, 0x580
	s_add_i32 s0, s0, 1
	s_mul_i32 s60, s0, 0x580
	s_mul_i32 s94, s0, 0x2c0
	s_addk_i32 s94, 0x1080
	s_mov_b32 s95, s94
	s_add_i32 s91, s57, s60
	s_branch .Lconv_entry
.Lconv_ret:
	v_readlane_b32 s24, v254, 0
	v_readlane_b32 s25, v254, 1
	v_readlane_b32 s26, v254, 2
	v_readlane_b32 s27, v254, 3
	v_readlane_b32 s28, v254, 4
	v_readlane_b32 s29, v254, 5
	v_readlane_b32 s30, v254, 6
	v_readlane_b32 s31, v254, 7
	s_mov_b32 s42, 0x8100
	s_ashr_i32 s50, s38, 31
	s_load_dword s0, s[88:89], 0xe8
	s_mul_i32 s51, s39, s38
	s_mov_b32 s52, 0xff800000
	s_mov_b32 s53, 0x41000000
	s_movk_i32 s54, 0xf800
	s_mov_b32 s55, -1
	s_waitcnt lgkmcnt(0)
	s_mul_i32 s51, s51, s0
.Lconv_skip:
.LBB0_625:
	s_mov_b64 s[4:5], s[88:89]
	s_getreg_b32 s0, hwreg(HW_REG_XCC_ID, 0, 4)
	v_mbcnt_lo_u32_b32 v1, -1, 0
	v_mbcnt_hi_u32_b32 v1, -1, v1
	s_waitcnt vmcnt(0)
	v_readlane_b32 s1, v255, 0
	s_waitcnt vmcnt(0) lgkmcnt(0)
	s_barrier
	v_cmp_eq_u32_e32 vcc, s1, v1
	s_and_saveexec_b64 s[2:3], vcc
	s_mov_b64 s[92:93], 0x48080
	s_cbranch_execz .LBB0_677
	v_readlane_b32 s1, v255, 32
	s_load_dwordx2 s[4:5], s[4:5], 0x98
	s_waitcnt vmcnt(0) expcnt(0) lgkmcnt(0)
	v_mov_b32_e32 v1, s1
	ds_read_b32 v3, v1
	v_readlane_b32 s1, v255, 33
	s_and_b32 s0, s0, 15
	s_waitcnt lgkmcnt(0)
	v_cmp_ne_u32_e32 vcc, 0, v3
	v_mov_b32_e32 v1, s1
	ds_read_b32 v2, v1
	s_cbranch_vccnz .LBB0_641
	s_add_u32 s8, s4, 0x1000
	s_addc_u32 s9, s5, 0
	s_add_u32 s10, s4, 0x1100
	s_addc_u32 s11, s5, 0
	s_add_u32 s14, s4, 0x1200
	s_addc_u32 s15, s5, 0
	s_add_u32 s30, s4, 0x1300
	s_addc_u32 s31, s5, 0
	s_mov_b32 s1, 1
	s_branch .LBB0_629
